# final RMSNorm hand-written: 4 rows per wave step, DPP reductions, gamma held in registers, next quad's loads issued before the current quad is reduced
# baseline (speedup 1.0000x reference)
; DI int get_tid() { int t = threadIdx.x; asm volatile("" : "+v"(t)); return t; }
; DI void phase_final(const Params& p) {
;   const int lane = get_tid() & 63, gw = blockIdx.x * 4 + (get_tid() >> 6), nw = gridDim.x * 4;
;   for (int pr = gw; pr < (NLAT >> 1); pr += nw) {
;     float* xr0 = p.out + (size_t)(2 * pr) * D;
;     float* xr1 = xr0 + D;
;     float4 v[2][4], gg[4];
;     float ss0 = 0.f, ss1 = 0.f;
; #pragma unroll
;     for (int i = 0; i < 4; ++i) {
;       typedef float f4ld __attribute__((ext_vector_type(4)));
;       const f4ld a_ = __builtin_nontemporal_load((const f4ld*)xr0 + lane + 64 * i), b_ = __builtin_nontemporal_load((const f4ld*)xr1 + lane + 64 * i);
;       v[0][i] = make_float4(a_[0], a_[1], a_[2], a_[3]); v[1][i] = make_float4(b_[0], b_[1], b_[2], b_[3]);
;     }
; #pragma unroll
;     for (int i = 0; i < 4; ++i) gg[i] = *(const float4*)(p.final_g + 4 * (lane + 64 * i));
; #pragma unroll
;     for (int i = 0; i < 4; ++i) {
;       ss0 += v[0][i].x * v[0][i].x + v[0][i].y * v[0][i].y + v[0][i].z * v[0][i].z + v[0][i].w * v[0][i].w;
;       ss1 += v[1][i].x * v[1][i].x + v[1][i].y * v[1][i].y + v[1][i].z * v[1][i].z + v[1][i].w * v[1][i].w;
;     }
;     ss0 = wave_sum(ss0); ss1 = wave_sum(ss1);
;     const float r0 = rsqrtf(ss0 * (1.0f / D) + 1e-6f), r1 = rsqrtf(ss1 * (1.0f / D) + 1e-6f);
; #pragma unroll
;     for (int i = 0; i < 4; ++i) {
;       typedef float f4nt __attribute__((ext_vector_type(4)));
;       const f4nt o0 = {v[0][i].x * r0 * gg[i].x, v[0][i].y * r0 * gg[i].y, v[0][i].z * r0 * gg[i].z, v[0][i].w * r0 * gg[i].w};
;       const f4nt o1 = {v[1][i].x * r1 * gg[i].x, v[1][i].y * r1 * gg[i].y, v[1][i].z * r1 * gg[i].z, v[1][i].w * r1 * gg[i].w};
;       __builtin_nontemporal_store(o0, (f4nt*)xr0 + lane + 64 * i);
;       __builtin_nontemporal_store(o1, (f4nt*)xr1 + lane + 64 * i);
;     }
;   }
; }
.LBB0_1758:
	v_mov_b32_e32 v1, v143
	s_movk_i32 s0, 0x4000
	v_ashrrev_i32_e32 v0, 6, v143
	v_add_u32_e32 v39, s34, v0
	v_cmp_gt_i32_e32 vcc, s0, v39
	s_and_saveexec_b64 s[0:1], vcc
	s_cbranch_execz .LBB0_1761
	v_cmp_lt_i32_e32 vcc, v202, v196
	v_and_b32_e32 v2, 63, v1
	v_mov_b32_e32 v33, 0
	v_cndmask_b32_e32 v1, v195, v202, vcc
	v_cmp_lt_i32_e32 vcc, v201, v196
	v_lshlrev_b32_e32 v46, 2, v1
	v_lshlrev_b32_e32 v32, 4, v2
	v_cndmask_b32_e32 v1, v195, v201, vcc
	v_cmp_lt_i32_e32 vcc, v200, v196
	v_lshlrev_b32_e32 v47, 2, v1
	v_readlane_b32 s0, v234, 14
	v_cndmask_b32_e32 v1, v195, v200, vcc
	v_cmp_lt_i32_e32 vcc, v199, v196
	v_lshlrev_b32_e32 v48, 2, v1
	v_lshl_add_u64 v[34:35], s[20:21], 0, v[32:33]
	v_cndmask_b32_e32 v1, v195, v199, vcc
	v_cmp_lt_i32_e32 vcc, v198, v196
	v_lshlrev_b32_e32 v49, 2, v1
	v_lshl_add_u32 v36, v0, 1, s0
	v_cndmask_b32_e32 v1, v195, v198, vcc
	v_cmp_lt_i32_e32 vcc, v197, v196
	v_lshlrev_b32_e32 v50, 2, v1
	s_mov_b64 s[2:3], 0
	v_cndmask_b32_e32 v1, v195, v197, vcc
	v_lshlrev_b32_e32 v51, 2, v1
	v_lshlrev_b32_e32 v32, 4, v2
	s_mov_b64 s[4:5], 0x1000
	s_mov_b32 s6, 0x3a800000
	v_mov_b32_e32 v38, 0x358637bd
	s_mov_b32 s7, 0x800000
	s_movk_i32 s8, 0x3fff
.LBB0_1760:
	s_branch .Lfn_entry
.Lfn_ret:
.LBB0_1761:
	s_endpgm
.Lfn_entry:
	v_lshrrev_b32_e32 v132, 6, v143
	v_readlane_b32 s0, v255, 0
	s_nop 0
	v_readfirstlane_b32 s1, v132
	s_nop 3
	s_lshl_b32 s54, s0, 2
	s_add_u32 s54, s54, s1
	s_lshl_b32 s55, s26, 2
	v_readlane_b32 s62, v255, 1
	v_readlane_b32 s63, v255, 2
	s_nop 3
	s_load_dwordx2 s[60:61], s[62:63], 0xe0
	v_and_b32_e32 v132, 63, v143
	v_lshlrev_b32_e32 v164, 4, v132
	v_mov_b32_e32 v160, v164
	v_add_u32_e32 v161, 0x1000, v164
	v_add_u32_e32 v162, 0x2000, v164
	v_add_u32_e32 v163, 0x3000, v164
	v_mov_b32_e32 v165, 0x358637bd
	s_waitcnt lgkmcnt(0)
	global_load_dwordx4 v[144:147], v164, s[60:61] offset:0
	global_load_dwordx4 v[148:151], v164, s[60:61] offset:1024
	global_load_dwordx4 v[152:155], v164, s[60:61] offset:2048
	global_load_dwordx4 v[156:159], v164, s[60:61] offset:3072
	s_min_u32 s0, s54, 8191
	s_lshl_b32 s0, s0, 14
	s_add_u32 s58, s22, s0
	s_addc_u32 s59, s23, 0
	global_load_dwordx4 v[0:3], v160, s[58:59] offset:0 nt
	global_load_dwordx4 v[4:7], v160, s[58:59] offset:1024 nt
	global_load_dwordx4 v[8:11], v160, s[58:59] offset:2048 nt
	global_load_dwordx4 v[12:15], v160, s[58:59] offset:3072 nt
	global_load_dwordx4 v[16:19], v161, s[58:59] offset:0 nt
	global_load_dwordx4 v[20:23], v161, s[58:59] offset:1024 nt
	global_load_dwordx4 v[24:27], v161, s[58:59] offset:2048 nt
	global_load_dwordx4 v[28:31], v161, s[58:59] offset:3072 nt
	global_load_dwordx4 v[32:35], v162, s[58:59] offset:0 nt
	global_load_dwordx4 v[36:39], v162, s[58:59] offset:1024 nt
	global_load_dwordx4 v[40:43], v162, s[58:59] offset:2048 nt
	global_load_dwordx4 v[44:47], v162, s[58:59] offset:3072 nt
	global_load_dwordx4 v[48:51], v163, s[58:59] offset:0 nt
	global_load_dwordx4 v[52:55], v163, s[58:59] offset:1024 nt
	global_load_dwordx4 v[56:59], v163, s[58:59] offset:2048 nt
	global_load_dwordx4 v[60:63], v163, s[58:59] offset:3072 nt
.Lnm_floop_23:
	s_add_u32 s56, s54, s55
	s_min_u32 s0, s56, 8191
	s_lshl_b32 s0, s0, 14
	s_add_u32 s58, s22, s0
	s_addc_u32 s59, s23, 0
	global_load_dwordx4 v[64:67], v160, s[58:59] offset:0 nt
	global_load_dwordx4 v[68:71], v160, s[58:59] offset:1024 nt
	global_load_dwordx4 v[72:75], v160, s[58:59] offset:2048 nt
	global_load_dwordx4 v[76:79], v160, s[58:59] offset:3072 nt
	global_load_dwordx4 v[80:83], v161, s[58:59] offset:0 nt
	global_load_dwordx4 v[84:87], v161, s[58:59] offset:1024 nt
	global_load_dwordx4 v[88:91], v161, s[58:59] offset:2048 nt
	global_load_dwordx4 v[92:95], v161, s[58:59] offset:3072 nt
	global_load_dwordx4 v[96:99], v162, s[58:59] offset:0 nt
	global_load_dwordx4 v[100:103], v162, s[58:59] offset:1024 nt
	global_load_dwordx4 v[104:107], v162, s[58:59] offset:2048 nt
	global_load_dwordx4 v[108:111], v162, s[58:59] offset:3072 nt
	global_load_dwordx4 v[112:115], v163, s[58:59] offset:0 nt
	global_load_dwordx4 v[116:119], v163, s[58:59] offset:1024 nt
	global_load_dwordx4 v[120:123], v163, s[58:59] offset:2048 nt
	global_load_dwordx4 v[124:127], v163, s[58:59] offset:3072 nt
	s_lshl_b32 s0, s54, 14
	s_add_u32 s12, s22, s0
	s_addc_u32 s13, s23, 0
	s_waitcnt vmcnt(28)
	v_mul_f32_e32 v128, v0, v0
	v_fmac_f32_e32 v128, v1, v1
	v_fmac_f32_e32 v128, v2, v2
	v_fmac_f32_e32 v128, v3, v3
	v_fmac_f32_e32 v128, v4, v4
	v_fmac_f32_e32 v128, v5, v5
	v_fmac_f32_e32 v128, v6, v6
	v_fmac_f32_e32 v128, v7, v7
	v_fmac_f32_e32 v128, v8, v8
	v_fmac_f32_e32 v128, v9, v9
	v_fmac_f32_e32 v128, v10, v10
	v_fmac_f32_e32 v128, v11, v11
	v_fmac_f32_e32 v128, v12, v12
	v_fmac_f32_e32 v128, v13, v13
	v_fmac_f32_e32 v128, v14, v14
	v_fmac_f32_e32 v128, v15, v15
	s_waitcnt vmcnt(24)
	v_mul_f32_e32 v129, v16, v16
	v_fmac_f32_e32 v129, v17, v17
	v_fmac_f32_e32 v129, v18, v18
	v_fmac_f32_e32 v129, v19, v19
	v_fmac_f32_e32 v129, v20, v20
	v_fmac_f32_e32 v129, v21, v21
	v_fmac_f32_e32 v129, v22, v22
	v_fmac_f32_e32 v129, v23, v23
	v_fmac_f32_e32 v129, v24, v24
	v_fmac_f32_e32 v129, v25, v25
	v_fmac_f32_e32 v129, v26, v26
	v_fmac_f32_e32 v129, v27, v27
	v_fmac_f32_e32 v129, v28, v28
	v_fmac_f32_e32 v129, v29, v29
	v_fmac_f32_e32 v129, v30, v30
	v_fmac_f32_e32 v129, v31, v31
	s_waitcnt vmcnt(20)
	v_mul_f32_e32 v130, v32, v32
	v_fmac_f32_e32 v130, v33, v33
	v_fmac_f32_e32 v130, v34, v34
	v_fmac_f32_e32 v130, v35, v35
	v_fmac_f32_e32 v130, v36, v36
	v_fmac_f32_e32 v130, v37, v37
	v_fmac_f32_e32 v130, v38, v38
	v_fmac_f32_e32 v130, v39, v39
	v_fmac_f32_e32 v130, v40, v40
	v_fmac_f32_e32 v130, v41, v41
	v_fmac_f32_e32 v130, v42, v42
	v_fmac_f32_e32 v130, v43, v43
	v_fmac_f32_e32 v130, v44, v44
	v_fmac_f32_e32 v130, v45, v45
	v_fmac_f32_e32 v130, v46, v46
	v_fmac_f32_e32 v130, v47, v47
	s_waitcnt vmcnt(16)
; DI void phase_final(const Params& p) {
;     ...
;     for (int i = 0; i < 4; ++i) {
;       ss0 += v[0][i].x * v[0][i].x + v[0][i].y * v[0][i].y + v[0][i].z * v[0][i].z + v[0][i].w * v[0][i].w;
;       ss1 += v[1][i].x * v[1][i].x + v[1][i].y * v[1][i].y + v[1][i].z * v[1][i].z + v[1][i].w * v[1][i].w;
;     }
;     ss0 = wave_sum(ss0); ss1 = wave_sum(ss1);
;     const float r0 = rsqrtf(ss0 * (1.0f / D) + 1e-6f), r1 = rsqrtf(ss1 * (1.0f / D) + 1e-6f);
; #pragma unroll
;     for (int i = 0; i < 4; ++i) {
;       typedef float f4nt __attribute__((ext_vector_type(4)));
;       const f4nt o0 = {v[0][i].x * r0 * gg[i].x, v[0][i].y * r0 * gg[i].y, v[0][i].z * r0 * gg[i].z, v[0][i].w * r0 * gg[i].w};
;       const f4nt o1 = {v[1][i].x * r1 * gg[i].x, v[1][i].y * r1 * gg[i].y, v[1][i].z * r1 * gg[i].z, v[1][i].w * r1 * gg[i].w};
;       __builtin_nontemporal_store(o0, (f4nt*)xr0 + lane + 64 * i);
;       __builtin_nontemporal_store(o1, (f4nt*)xr1 + lane + 64 * i);
;     }
	v_mul_f32_e32 v131, v48, v48
	v_fmac_f32_e32 v131, v49, v49
	v_fmac_f32_e32 v131, v50, v50
	v_fmac_f32_e32 v131, v51, v51
	v_fmac_f32_e32 v131, v52, v52
	v_fmac_f32_e32 v131, v53, v53
	v_fmac_f32_e32 v131, v54, v54
	v_fmac_f32_e32 v131, v55, v55
	v_fmac_f32_e32 v131, v56, v56
	v_fmac_f32_e32 v131, v57, v57
	v_fmac_f32_e32 v131, v58, v58
	v_fmac_f32_e32 v131, v59, v59
	v_fmac_f32_e32 v131, v60, v60
	v_fmac_f32_e32 v131, v61, v61
	v_fmac_f32_e32 v131, v62, v62
	v_fmac_f32_e32 v131, v63, v63
	v_add_f32_dpp v128, v128, v128 quad_perm:[1,0,3,2] row_mask:0xf bank_mask:0xf
	v_add_f32_dpp v129, v129, v129 quad_perm:[1,0,3,2] row_mask:0xf bank_mask:0xf
	v_add_f32_dpp v130, v130, v130 quad_perm:[1,0,3,2] row_mask:0xf bank_mask:0xf
	v_add_f32_dpp v131, v131, v131 quad_perm:[1,0,3,2] row_mask:0xf bank_mask:0xf
	v_add_f32_dpp v128, v128, v128 quad_perm:[2,3,0,1] row_mask:0xf bank_mask:0xf
	v_add_f32_dpp v129, v129, v129 quad_perm:[2,3,0,1] row_mask:0xf bank_mask:0xf
	v_add_f32_dpp v130, v130, v130 quad_perm:[2,3,0,1] row_mask:0xf bank_mask:0xf
	v_add_f32_dpp v131, v131, v131 quad_perm:[2,3,0,1] row_mask:0xf bank_mask:0xf
	v_add_f32_dpp v128, v128, v128 row_half_mirror row_mask:0xf bank_mask:0xf
	v_add_f32_dpp v129, v129, v129 row_half_mirror row_mask:0xf bank_mask:0xf
	v_add_f32_dpp v130, v130, v130 row_half_mirror row_mask:0xf bank_mask:0xf
	v_add_f32_dpp v131, v131, v131 row_half_mirror row_mask:0xf bank_mask:0xf
	v_add_f32_dpp v128, v128, v128 row_mirror row_mask:0xf bank_mask:0xf
	v_add_f32_dpp v129, v129, v129 row_mirror row_mask:0xf bank_mask:0xf
	v_add_f32_dpp v130, v130, v130 row_mirror row_mask:0xf bank_mask:0xf
	v_add_f32_dpp v131, v131, v131 row_mirror row_mask:0xf bank_mask:0xf
	s_nop 1
	v_readlane_b32 s64, v128, 0
	v_readlane_b32 s65, v128, 16
	v_readlane_b32 s66, v128, 32
	v_readlane_b32 s67, v128, 48
	s_nop 1
	v_mov_b32_e32 v132, s64
	v_add_f32_e32 v132, s65, v132
	v_add_f32_e32 v132, s66, v132
	v_add_f32_e32 v132, s67, v132
	v_readlane_b32 s64, v129, 0
	v_readlane_b32 s65, v129, 16
	v_readlane_b32 s66, v129, 32
	v_readlane_b32 s67, v129, 48
	s_nop 1
	v_mov_b32_e32 v133, s64
	v_add_f32_e32 v133, s65, v133
	v_add_f32_e32 v133, s66, v133
	v_add_f32_e32 v133, s67, v133
	v_readlane_b32 s64, v130, 0
	v_readlane_b32 s65, v130, 16
	v_readlane_b32 s66, v130, 32
	v_readlane_b32 s67, v130, 48
	s_nop 1
	v_mov_b32_e32 v134, s64
	v_add_f32_e32 v134, s65, v134
	v_add_f32_e32 v134, s66, v134
	v_add_f32_e32 v134, s67, v134
	v_readlane_b32 s64, v131, 0
	v_readlane_b32 s65, v131, 16
	v_readlane_b32 s66, v131, 32
	v_readlane_b32 s67, v131, 48
	s_nop 1
	v_mov_b32_e32 v135, s64
	v_add_f32_e32 v135, s65, v135
	v_add_f32_e32 v135, s66, v135
	v_add_f32_e32 v135, s67, v135
	s_mov_b32 s0, 0x3a800000
	v_fma_f32 v132, v132, s0, v165
	v_fma_f32 v133, v133, s0, v165
	v_fma_f32 v134, v134, s0, v165
	v_fma_f32 v135, v135, s0, v165
	v_rsq_f32_e32 v128, v132
	v_rsq_f32_e32 v129, v133
	v_rsq_f32_e32 v130, v134
	v_rsq_f32_e32 v131, v135
	v_mul_f32_e32 v0, v0, v128
	v_mul_f32_e32 v1, v1, v128
	v_mul_f32_e32 v2, v2, v128
	v_mul_f32_e32 v3, v3, v128
	v_mul_f32_e32 v0, v0, v144
	v_mul_f32_e32 v1, v1, v145
	v_mul_f32_e32 v2, v2, v146
	v_mul_f32_e32 v3, v3, v147
	global_store_dwordx4 v160, v[0:3], s[12:13] offset:0 nt
	v_mul_f32_e32 v4, v4, v128
	v_mul_f32_e32 v5, v5, v128
	v_mul_f32_e32 v6, v6, v128
	v_mul_f32_e32 v7, v7, v128
	v_mul_f32_e32 v4, v4, v148
	v_mul_f32_e32 v5, v5, v149
	v_mul_f32_e32 v6, v6, v150
	v_mul_f32_e32 v7, v7, v151
	global_store_dwordx4 v160, v[4:7], s[12:13] offset:1024 nt
	v_mul_f32_e32 v8, v8, v128
	v_mul_f32_e32 v9, v9, v128
	v_mul_f32_e32 v10, v10, v128
	v_mul_f32_e32 v11, v11, v128
	v_mul_f32_e32 v8, v8, v152
	v_mul_f32_e32 v9, v9, v153
	v_mul_f32_e32 v10, v10, v154
	v_mul_f32_e32 v11, v11, v155
	global_store_dwordx4 v160, v[8:11], s[12:13] offset:2048 nt
	v_mul_f32_e32 v12, v12, v128
	v_mul_f32_e32 v13, v13, v128
	v_mul_f32_e32 v14, v14, v128
	v_mul_f32_e32 v15, v15, v128
	v_mul_f32_e32 v12, v12, v156
	v_mul_f32_e32 v13, v13, v157
	v_mul_f32_e32 v14, v14, v158
	v_mul_f32_e32 v15, v15, v159
	global_store_dwordx4 v160, v[12:15], s[12:13] offset:3072 nt
	v_mul_f32_e32 v16, v16, v129
	v_mul_f32_e32 v17, v17, v129
	v_mul_f32_e32 v18, v18, v129
	v_mul_f32_e32 v19, v19, v129
	v_mul_f32_e32 v16, v16, v144
	v_mul_f32_e32 v17, v17, v145
	v_mul_f32_e32 v18, v18, v146
	v_mul_f32_e32 v19, v19, v147
	global_store_dwordx4 v161, v[16:19], s[12:13] offset:0 nt
	v_mul_f32_e32 v20, v20, v129
	v_mul_f32_e32 v21, v21, v129
	v_mul_f32_e32 v22, v22, v129
	v_mul_f32_e32 v23, v23, v129
	v_mul_f32_e32 v20, v20, v148
	v_mul_f32_e32 v21, v21, v149
	v_mul_f32_e32 v22, v22, v150
	v_mul_f32_e32 v23, v23, v151
	global_store_dwordx4 v161, v[20:23], s[12:13] offset:1024 nt
	v_mul_f32_e32 v24, v24, v129
	v_mul_f32_e32 v25, v25, v129
	v_mul_f32_e32 v26, v26, v129
	v_mul_f32_e32 v27, v27, v129
	v_mul_f32_e32 v24, v24, v152
	v_mul_f32_e32 v25, v25, v153
	v_mul_f32_e32 v26, v26, v154
	v_mul_f32_e32 v27, v27, v155
	global_store_dwordx4 v161, v[24:27], s[12:13] offset:2048 nt
	v_mul_f32_e32 v28, v28, v129
	v_mul_f32_e32 v29, v29, v129
	v_mul_f32_e32 v30, v30, v129
	v_mul_f32_e32 v31, v31, v129
	v_mul_f32_e32 v28, v28, v156
	v_mul_f32_e32 v29, v29, v157
	v_mul_f32_e32 v30, v30, v158
	v_mul_f32_e32 v31, v31, v159
	global_store_dwordx4 v161, v[28:31], s[12:13] offset:3072 nt
	v_mul_f32_e32 v32, v32, v130
	v_mul_f32_e32 v33, v33, v130
	v_mul_f32_e32 v34, v34, v130
	v_mul_f32_e32 v35, v35, v130
	v_mul_f32_e32 v32, v32, v144
	v_mul_f32_e32 v33, v33, v145
	v_mul_f32_e32 v34, v34, v146
	v_mul_f32_e32 v35, v35, v147
	global_store_dwordx4 v162, v[32:35], s[12:13] offset:0 nt
	v_mul_f32_e32 v36, v36, v130
; DI void phase_final(const Params& p) {
;     ...
;   for (int pr = gw; pr < (NLAT >> 1); pr += nw) {
;     float* xr0 = p.out + (size_t)(2 * pr) * D;
;     float* xr1 = xr0 + D;
;     float4 v[2][4], gg[4];
;     float ss0 = 0.f, ss1 = 0.f;
; #pragma unroll
;     for (int i = 0; i < 4; ++i) {
;       typedef float f4ld __attribute__((ext_vector_type(4)));
;       const f4ld a_ = __builtin_nontemporal_load((const f4ld*)xr0 + lane + 64 * i), b_ = __builtin_nontemporal_load((const f4ld*)xr1 + lane + 64 * i);
;       v[0][i] = make_float4(a_[0], a_[1], a_[2], a_[3]); v[1][i] = make_float4(b_[0], b_[1], b_[2], b_[3]);
;     }
; #pragma unroll
;     for (int i = 0; i < 4; ++i) gg[i] = *(const float4*)(p.final_g + 4 * (lane + 64 * i));
; #pragma unroll
;     for (int i = 0; i < 4; ++i) {
;       ss0 += v[0][i].x * v[0][i].x + v[0][i].y * v[0][i].y + v[0][i].z * v[0][i].z + v[0][i].w * v[0][i].w;
;       ss1 += v[1][i].x * v[1][i].x + v[1][i].y * v[1][i].y + v[1][i].z * v[1][i].z + v[1][i].w * v[1][i].w;
;     }
;     ss0 = wave_sum(ss0); ss1 = wave_sum(ss1);
;     const float r0 = rsqrtf(ss0 * (1.0f / D) + 1e-6f), r1 = rsqrtf(ss1 * (1.0f / D) + 1e-6f);
; #pragma unroll
;     for (int i = 0; i < 4; ++i) {
;       typedef float f4nt __attribute__((ext_vector_type(4)));
;       const f4nt o0 = {v[0][i].x * r0 * gg[i].x, v[0][i].y * r0 * gg[i].y, v[0][i].z * r0 * gg[i].z, v[0][i].w * r0 * gg[i].w};
;       const f4nt o1 = {v[1][i].x * r1 * gg[i].x, v[1][i].y * r1 * gg[i].y, v[1][i].z * r1 * gg[i].z, v[1][i].w * r1 * gg[i].w};
;       __builtin_nontemporal_store(o0, (f4nt*)xr0 + lane + 64 * i);
;       __builtin_nontemporal_store(o1, (f4nt*)xr1 + lane + 64 * i);
;     }
	v_mul_f32_e32 v37, v37, v130
	v_mul_f32_e32 v38, v38, v130
	v_mul_f32_e32 v39, v39, v130
	v_mul_f32_e32 v36, v36, v148
	v_mul_f32_e32 v37, v37, v149
	v_mul_f32_e32 v38, v38, v150
	v_mul_f32_e32 v39, v39, v151
	global_store_dwordx4 v162, v[36:39], s[12:13] offset:1024 nt
	v_mul_f32_e32 v40, v40, v130
	v_mul_f32_e32 v41, v41, v130
	v_mul_f32_e32 v42, v42, v130
	v_mul_f32_e32 v43, v43, v130
	v_mul_f32_e32 v40, v40, v152
	v_mul_f32_e32 v41, v41, v153
	v_mul_f32_e32 v42, v42, v154
	v_mul_f32_e32 v43, v43, v155
	global_store_dwordx4 v162, v[40:43], s[12:13] offset:2048 nt
	v_mul_f32_e32 v44, v44, v130
	v_mul_f32_e32 v45, v45, v130
	v_mul_f32_e32 v46, v46, v130
	v_mul_f32_e32 v47, v47, v130
	v_mul_f32_e32 v44, v44, v156
	v_mul_f32_e32 v45, v45, v157
	v_mul_f32_e32 v46, v46, v158
	v_mul_f32_e32 v47, v47, v159
	global_store_dwordx4 v162, v[44:47], s[12:13] offset:3072 nt
	v_mul_f32_e32 v48, v48, v131
	v_mul_f32_e32 v49, v49, v131
	v_mul_f32_e32 v50, v50, v131
	v_mul_f32_e32 v51, v51, v131
	v_mul_f32_e32 v48, v48, v144
	v_mul_f32_e32 v49, v49, v145
	v_mul_f32_e32 v50, v50, v146
	v_mul_f32_e32 v51, v51, v147
	global_store_dwordx4 v163, v[48:51], s[12:13] offset:0 nt
	v_mul_f32_e32 v52, v52, v131
	v_mul_f32_e32 v53, v53, v131
	v_mul_f32_e32 v54, v54, v131
	v_mul_f32_e32 v55, v55, v131
	v_mul_f32_e32 v52, v52, v148
	v_mul_f32_e32 v53, v53, v149
	v_mul_f32_e32 v54, v54, v150
	v_mul_f32_e32 v55, v55, v151
	global_store_dwordx4 v163, v[52:55], s[12:13] offset:1024 nt
	v_mul_f32_e32 v56, v56, v131
	v_mul_f32_e32 v57, v57, v131
	v_mul_f32_e32 v58, v58, v131
	v_mul_f32_e32 v59, v59, v131
	v_mul_f32_e32 v56, v56, v152
	v_mul_f32_e32 v57, v57, v153
	v_mul_f32_e32 v58, v58, v154
	v_mul_f32_e32 v59, v59, v155
	global_store_dwordx4 v163, v[56:59], s[12:13] offset:2048 nt
	v_mul_f32_e32 v60, v60, v131
	v_mul_f32_e32 v61, v61, v131
	v_mul_f32_e32 v62, v62, v131
	v_mul_f32_e32 v63, v63, v131
	v_mul_f32_e32 v60, v60, v156
	v_mul_f32_e32 v61, v61, v157
	v_mul_f32_e32 v62, v62, v158
	v_mul_f32_e32 v63, v63, v159
	global_store_dwordx4 v163, v[60:63], s[12:13] offset:3072 nt
	s_add_u32 s54, s54, s55
	s_cmpk_ge_u32 s54, 8192
	s_cbranch_scc1 .Lnm_fdone_24
	s_add_u32 s56, s54, s55
	s_min_u32 s0, s56, 8191
	s_lshl_b32 s0, s0, 14
	s_add_u32 s58, s22, s0
	s_addc_u32 s59, s23, 0
	global_load_dwordx4 v[0:3], v160, s[58:59] offset:0 nt
	global_load_dwordx4 v[4:7], v160, s[58:59] offset:1024 nt
	global_load_dwordx4 v[8:11], v160, s[58:59] offset:2048 nt
	global_load_dwordx4 v[12:15], v160, s[58:59] offset:3072 nt
	global_load_dwordx4 v[16:19], v161, s[58:59] offset:0 nt
	global_load_dwordx4 v[20:23], v161, s[58:59] offset:1024 nt
	global_load_dwordx4 v[24:27], v161, s[58:59] offset:2048 nt
	global_load_dwordx4 v[28:31], v161, s[58:59] offset:3072 nt
	global_load_dwordx4 v[32:35], v162, s[58:59] offset:0 nt
	global_load_dwordx4 v[36:39], v162, s[58:59] offset:1024 nt
	global_load_dwordx4 v[40:43], v162, s[58:59] offset:2048 nt
	global_load_dwordx4 v[44:47], v162, s[58:59] offset:3072 nt
	global_load_dwordx4 v[48:51], v163, s[58:59] offset:0 nt
	global_load_dwordx4 v[52:55], v163, s[58:59] offset:1024 nt
	global_load_dwordx4 v[56:59], v163, s[58:59] offset:2048 nt
	global_load_dwordx4 v[60:63], v163, s[58:59] offset:3072 nt
	s_lshl_b32 s0, s54, 14
	s_add_u32 s12, s22, s0
	s_addc_u32 s13, s23, 0
	s_waitcnt vmcnt(28)
	v_mul_f32_e32 v128, v64, v64
	v_fmac_f32_e32 v128, v65, v65
	v_fmac_f32_e32 v128, v66, v66
	v_fmac_f32_e32 v128, v67, v67
	v_fmac_f32_e32 v128, v68, v68
	v_fmac_f32_e32 v128, v69, v69
	v_fmac_f32_e32 v128, v70, v70
	v_fmac_f32_e32 v128, v71, v71
	v_fmac_f32_e32 v128, v72, v72
	v_fmac_f32_e32 v128, v73, v73
	v_fmac_f32_e32 v128, v74, v74
	v_fmac_f32_e32 v128, v75, v75
	v_fmac_f32_e32 v128, v76, v76
	v_fmac_f32_e32 v128, v77, v77
	v_fmac_f32_e32 v128, v78, v78
	v_fmac_f32_e32 v128, v79, v79
	s_waitcnt vmcnt(24)
	v_mul_f32_e32 v129, v80, v80
	v_fmac_f32_e32 v129, v81, v81
	v_fmac_f32_e32 v129, v82, v82
	v_fmac_f32_e32 v129, v83, v83
	v_fmac_f32_e32 v129, v84, v84
	v_fmac_f32_e32 v129, v85, v85
	v_fmac_f32_e32 v129, v86, v86
	v_fmac_f32_e32 v129, v87, v87
	v_fmac_f32_e32 v129, v88, v88
	v_fmac_f32_e32 v129, v89, v89
	v_fmac_f32_e32 v129, v90, v90
	v_fmac_f32_e32 v129, v91, v91
	v_fmac_f32_e32 v129, v92, v92
	v_fmac_f32_e32 v129, v93, v93
	v_fmac_f32_e32 v129, v94, v94
	v_fmac_f32_e32 v129, v95, v95
	s_waitcnt vmcnt(20)
	v_mul_f32_e32 v130, v96, v96
	v_fmac_f32_e32 v130, v97, v97
	v_fmac_f32_e32 v130, v98, v98
	v_fmac_f32_e32 v130, v99, v99
	v_fmac_f32_e32 v130, v100, v100
	v_fmac_f32_e32 v130, v101, v101
	v_fmac_f32_e32 v130, v102, v102
	v_fmac_f32_e32 v130, v103, v103
	v_fmac_f32_e32 v130, v104, v104
	v_fmac_f32_e32 v130, v105, v105
	v_fmac_f32_e32 v130, v106, v106
	v_fmac_f32_e32 v130, v107, v107
	v_fmac_f32_e32 v130, v108, v108
	v_fmac_f32_e32 v130, v109, v109
	v_fmac_f32_e32 v130, v110, v110
	v_fmac_f32_e32 v130, v111, v111
	s_waitcnt vmcnt(16)
; DI void phase_final(const Params& p) {
;     ...
;     for (int i = 0; i < 4; ++i) {
;       ss0 += v[0][i].x * v[0][i].x + v[0][i].y * v[0][i].y + v[0][i].z * v[0][i].z + v[0][i].w * v[0][i].w;
;       ss1 += v[1][i].x * v[1][i].x + v[1][i].y * v[1][i].y + v[1][i].z * v[1][i].z + v[1][i].w * v[1][i].w;
;     }
;     ss0 = wave_sum(ss0); ss1 = wave_sum(ss1);
;     const float r0 = rsqrtf(ss0 * (1.0f / D) + 1e-6f), r1 = rsqrtf(ss1 * (1.0f / D) + 1e-6f);
; #pragma unroll
;     for (int i = 0; i < 4; ++i) {
;       typedef float f4nt __attribute__((ext_vector_type(4)));
;       const f4nt o0 = {v[0][i].x * r0 * gg[i].x, v[0][i].y * r0 * gg[i].y, v[0][i].z * r0 * gg[i].z, v[0][i].w * r0 * gg[i].w};
;       const f4nt o1 = {v[1][i].x * r1 * gg[i].x, v[1][i].y * r1 * gg[i].y, v[1][i].z * r1 * gg[i].z, v[1][i].w * r1 * gg[i].w};
;       __builtin_nontemporal_store(o0, (f4nt*)xr0 + lane + 64 * i);
;       __builtin_nontemporal_store(o1, (f4nt*)xr1 + lane + 64 * i);
;     }
	v_mul_f32_e32 v131, v112, v112
	v_fmac_f32_e32 v131, v113, v113
	v_fmac_f32_e32 v131, v114, v114
	v_fmac_f32_e32 v131, v115, v115
	v_fmac_f32_e32 v131, v116, v116
	v_fmac_f32_e32 v131, v117, v117
	v_fmac_f32_e32 v131, v118, v118
	v_fmac_f32_e32 v131, v119, v119
	v_fmac_f32_e32 v131, v120, v120
	v_fmac_f32_e32 v131, v121, v121
	v_fmac_f32_e32 v131, v122, v122
	v_fmac_f32_e32 v131, v123, v123
	v_fmac_f32_e32 v131, v124, v124
	v_fmac_f32_e32 v131, v125, v125
	v_fmac_f32_e32 v131, v126, v126
	v_fmac_f32_e32 v131, v127, v127
	v_add_f32_dpp v128, v128, v128 quad_perm:[1,0,3,2] row_mask:0xf bank_mask:0xf
	v_add_f32_dpp v129, v129, v129 quad_perm:[1,0,3,2] row_mask:0xf bank_mask:0xf
	v_add_f32_dpp v130, v130, v130 quad_perm:[1,0,3,2] row_mask:0xf bank_mask:0xf
	v_add_f32_dpp v131, v131, v131 quad_perm:[1,0,3,2] row_mask:0xf bank_mask:0xf
	v_add_f32_dpp v128, v128, v128 quad_perm:[2,3,0,1] row_mask:0xf bank_mask:0xf
	v_add_f32_dpp v129, v129, v129 quad_perm:[2,3,0,1] row_mask:0xf bank_mask:0xf
	v_add_f32_dpp v130, v130, v130 quad_perm:[2,3,0,1] row_mask:0xf bank_mask:0xf
	v_add_f32_dpp v131, v131, v131 quad_perm:[2,3,0,1] row_mask:0xf bank_mask:0xf
	v_add_f32_dpp v128, v128, v128 row_half_mirror row_mask:0xf bank_mask:0xf
	v_add_f32_dpp v129, v129, v129 row_half_mirror row_mask:0xf bank_mask:0xf
	v_add_f32_dpp v130, v130, v130 row_half_mirror row_mask:0xf bank_mask:0xf
	v_add_f32_dpp v131, v131, v131 row_half_mirror row_mask:0xf bank_mask:0xf
	v_add_f32_dpp v128, v128, v128 row_mirror row_mask:0xf bank_mask:0xf
	v_add_f32_dpp v129, v129, v129 row_mirror row_mask:0xf bank_mask:0xf
	v_add_f32_dpp v130, v130, v130 row_mirror row_mask:0xf bank_mask:0xf
	v_add_f32_dpp v131, v131, v131 row_mirror row_mask:0xf bank_mask:0xf
	s_nop 1
	v_readlane_b32 s64, v128, 0
	v_readlane_b32 s65, v128, 16
	v_readlane_b32 s66, v128, 32
	v_readlane_b32 s67, v128, 48
	s_nop 1
	v_mov_b32_e32 v132, s64
	v_add_f32_e32 v132, s65, v132
	v_add_f32_e32 v132, s66, v132
	v_add_f32_e32 v132, s67, v132
	v_readlane_b32 s64, v129, 0
	v_readlane_b32 s65, v129, 16
	v_readlane_b32 s66, v129, 32
	v_readlane_b32 s67, v129, 48
	s_nop 1
	v_mov_b32_e32 v133, s64
	v_add_f32_e32 v133, s65, v133
	v_add_f32_e32 v133, s66, v133
	v_add_f32_e32 v133, s67, v133
	v_readlane_b32 s64, v130, 0
	v_readlane_b32 s65, v130, 16
	v_readlane_b32 s66, v130, 32
	v_readlane_b32 s67, v130, 48
	s_nop 1
	v_mov_b32_e32 v134, s64
	v_add_f32_e32 v134, s65, v134
	v_add_f32_e32 v134, s66, v134
	v_add_f32_e32 v134, s67, v134
	v_readlane_b32 s64, v131, 0
	v_readlane_b32 s65, v131, 16
	v_readlane_b32 s66, v131, 32
	v_readlane_b32 s67, v131, 48
	s_nop 1
	v_mov_b32_e32 v135, s64
	v_add_f32_e32 v135, s65, v135
	v_add_f32_e32 v135, s66, v135
	v_add_f32_e32 v135, s67, v135
	s_mov_b32 s0, 0x3a800000
	v_fma_f32 v132, v132, s0, v165
	v_fma_f32 v133, v133, s0, v165
	v_fma_f32 v134, v134, s0, v165
	v_fma_f32 v135, v135, s0, v165
	v_rsq_f32_e32 v128, v132
	v_rsq_f32_e32 v129, v133
	v_rsq_f32_e32 v130, v134
	v_rsq_f32_e32 v131, v135
	v_mul_f32_e32 v64, v64, v128
	v_mul_f32_e32 v65, v65, v128
	v_mul_f32_e32 v66, v66, v128
	v_mul_f32_e32 v67, v67, v128
	v_mul_f32_e32 v64, v64, v144
	v_mul_f32_e32 v65, v65, v145
	v_mul_f32_e32 v66, v66, v146
	v_mul_f32_e32 v67, v67, v147
	global_store_dwordx4 v160, v[64:67], s[12:13] offset:0 nt
	v_mul_f32_e32 v68, v68, v128
	v_mul_f32_e32 v69, v69, v128
	v_mul_f32_e32 v70, v70, v128
	v_mul_f32_e32 v71, v71, v128
	v_mul_f32_e32 v68, v68, v148
	v_mul_f32_e32 v69, v69, v149
	v_mul_f32_e32 v70, v70, v150
	v_mul_f32_e32 v71, v71, v151
	global_store_dwordx4 v160, v[68:71], s[12:13] offset:1024 nt
	v_mul_f32_e32 v72, v72, v128
	v_mul_f32_e32 v73, v73, v128
	v_mul_f32_e32 v74, v74, v128
	v_mul_f32_e32 v75, v75, v128
	v_mul_f32_e32 v72, v72, v152
	v_mul_f32_e32 v73, v73, v153
	v_mul_f32_e32 v74, v74, v154
	v_mul_f32_e32 v75, v75, v155
	global_store_dwordx4 v160, v[72:75], s[12:13] offset:2048 nt
	v_mul_f32_e32 v76, v76, v128
	v_mul_f32_e32 v77, v77, v128
	v_mul_f32_e32 v78, v78, v128
	v_mul_f32_e32 v79, v79, v128
	v_mul_f32_e32 v76, v76, v156
; DI void phase_final(const Params& p) {
;     ...
; #pragma unroll
;     for (int i = 0; i < 4; ++i) {
;       typedef float f4nt __attribute__((ext_vector_type(4)));
;       const f4nt o0 = {v[0][i].x * r0 * gg[i].x, v[0][i].y * r0 * gg[i].y, v[0][i].z * r0 * gg[i].z, v[0][i].w * r0 * gg[i].w};
;       const f4nt o1 = {v[1][i].x * r1 * gg[i].x, v[1][i].y * r1 * gg[i].y, v[1][i].z * r1 * gg[i].z, v[1][i].w * r1 * gg[i].w};
;       __builtin_nontemporal_store(o0, (f4nt*)xr0 + lane + 64 * i);
;       __builtin_nontemporal_store(o1, (f4nt*)xr1 + lane + 64 * i);
;     }
	v_mul_f32_e32 v77, v77, v157
	v_mul_f32_e32 v78, v78, v158
	v_mul_f32_e32 v79, v79, v159
	global_store_dwordx4 v160, v[76:79], s[12:13] offset:3072 nt
	v_mul_f32_e32 v80, v80, v129
	v_mul_f32_e32 v81, v81, v129
	v_mul_f32_e32 v82, v82, v129
	v_mul_f32_e32 v83, v83, v129
	v_mul_f32_e32 v80, v80, v144
	v_mul_f32_e32 v81, v81, v145
	v_mul_f32_e32 v82, v82, v146
	v_mul_f32_e32 v83, v83, v147
	global_store_dwordx4 v161, v[80:83], s[12:13] offset:0 nt
	v_mul_f32_e32 v84, v84, v129
	v_mul_f32_e32 v85, v85, v129
	v_mul_f32_e32 v86, v86, v129
	v_mul_f32_e32 v87, v87, v129
	v_mul_f32_e32 v84, v84, v148
	v_mul_f32_e32 v85, v85, v149
	v_mul_f32_e32 v86, v86, v150
	v_mul_f32_e32 v87, v87, v151
	global_store_dwordx4 v161, v[84:87], s[12:13] offset:1024 nt
	v_mul_f32_e32 v88, v88, v129
	v_mul_f32_e32 v89, v89, v129
	v_mul_f32_e32 v90, v90, v129
	v_mul_f32_e32 v91, v91, v129
	v_mul_f32_e32 v88, v88, v152
	v_mul_f32_e32 v89, v89, v153
	v_mul_f32_e32 v90, v90, v154
	v_mul_f32_e32 v91, v91, v155
	global_store_dwordx4 v161, v[88:91], s[12:13] offset:2048 nt
	v_mul_f32_e32 v92, v92, v129
	v_mul_f32_e32 v93, v93, v129
	v_mul_f32_e32 v94, v94, v129
	v_mul_f32_e32 v95, v95, v129
	v_mul_f32_e32 v92, v92, v156
	v_mul_f32_e32 v93, v93, v157
	v_mul_f32_e32 v94, v94, v158
	v_mul_f32_e32 v95, v95, v159
	global_store_dwordx4 v161, v[92:95], s[12:13] offset:3072 nt
	v_mul_f32_e32 v96, v96, v130
	v_mul_f32_e32 v97, v97, v130
	v_mul_f32_e32 v98, v98, v130
	v_mul_f32_e32 v99, v99, v130
	v_mul_f32_e32 v96, v96, v144
	v_mul_f32_e32 v97, v97, v145
	v_mul_f32_e32 v98, v98, v146
	v_mul_f32_e32 v99, v99, v147
	global_store_dwordx4 v162, v[96:99], s[12:13] offset:0 nt
	v_mul_f32_e32 v100, v100, v130
	v_mul_f32_e32 v101, v101, v130
	v_mul_f32_e32 v102, v102, v130
	v_mul_f32_e32 v103, v103, v130
	v_mul_f32_e32 v100, v100, v148
	v_mul_f32_e32 v101, v101, v149
	v_mul_f32_e32 v102, v102, v150
	v_mul_f32_e32 v103, v103, v151
	global_store_dwordx4 v162, v[100:103], s[12:13] offset:1024 nt
	v_mul_f32_e32 v104, v104, v130
	v_mul_f32_e32 v105, v105, v130
	v_mul_f32_e32 v106, v106, v130
	v_mul_f32_e32 v107, v107, v130
	v_mul_f32_e32 v104, v104, v152
	v_mul_f32_e32 v105, v105, v153
	v_mul_f32_e32 v106, v106, v154
	v_mul_f32_e32 v107, v107, v155
	global_store_dwordx4 v162, v[104:107], s[12:13] offset:2048 nt
	v_mul_f32_e32 v108, v108, v130
	v_mul_f32_e32 v109, v109, v130
	v_mul_f32_e32 v110, v110, v130
	v_mul_f32_e32 v111, v111, v130
	v_mul_f32_e32 v108, v108, v156
	v_mul_f32_e32 v109, v109, v157
	v_mul_f32_e32 v110, v110, v158
	v_mul_f32_e32 v111, v111, v159
	global_store_dwordx4 v162, v[108:111], s[12:13] offset:3072 nt
	v_mul_f32_e32 v112, v112, v131
	v_mul_f32_e32 v113, v113, v131
	v_mul_f32_e32 v114, v114, v131
	v_mul_f32_e32 v115, v115, v131
	v_mul_f32_e32 v112, v112, v144
	v_mul_f32_e32 v113, v113, v145
	v_mul_f32_e32 v114, v114, v146
	v_mul_f32_e32 v115, v115, v147
	global_store_dwordx4 v163, v[112:115], s[12:13] offset:0 nt
	v_mul_f32_e32 v116, v116, v131
	v_mul_f32_e32 v117, v117, v131
	v_mul_f32_e32 v118, v118, v131
	v_mul_f32_e32 v119, v119, v131
	v_mul_f32_e32 v116, v116, v148
	v_mul_f32_e32 v117, v117, v149
	v_mul_f32_e32 v118, v118, v150
	v_mul_f32_e32 v119, v119, v151
	global_store_dwordx4 v163, v[116:119], s[12:13] offset:1024 nt
	v_mul_f32_e32 v120, v120, v131
	v_mul_f32_e32 v121, v121, v131
	v_mul_f32_e32 v122, v122, v131
	v_mul_f32_e32 v123, v123, v131
	v_mul_f32_e32 v120, v120, v152
	v_mul_f32_e32 v121, v121, v153
	v_mul_f32_e32 v122, v122, v154
	v_mul_f32_e32 v123, v123, v155
	global_store_dwordx4 v163, v[120:123], s[12:13] offset:2048 nt
	v_mul_f32_e32 v124, v124, v131
	v_mul_f32_e32 v125, v125, v131
	v_mul_f32_e32 v126, v126, v131
	v_mul_f32_e32 v127, v127, v131
	v_mul_f32_e32 v124, v124, v156
	v_mul_f32_e32 v125, v125, v157
	v_mul_f32_e32 v126, v126, v158
	v_mul_f32_e32 v127, v127, v159
	global_store_dwordx4 v163, v[124:127], s[12:13] offset:3072 nt
	s_add_u32 s54, s54, s55
	s_cmpk_ge_u32 s54, 8192
	s_cbranch_scc1 .Lnm_fdone_24
	s_branch .Lnm_floop_23
.Lnm_fdone_24:
	s_waitcnt vmcnt(0)
	s_branch .Lfn_ret
